# S5 mode-1 item loop: store-ack wait replaced by a same-size s_nop (code layout unchanged)
# speedup vs baseline: 1.0013x; 1.0002x over previous
.LBB0_639:
	s_or_b64 exec, exec, s[2:3]
	s_nop 0
	v_readfirstlane_b32 s28, v184
	s_add_i32 s28, s28, 0x100
	s_lshl_b32 s28, s28, 3
	s_add_i32 s28, s28, s29
	s_cmp_ge_u32 s28, s17
	s_cbranch_scc1 .LBB0_654
	v_mov_b32_e32 v105, s28
